# MLA unit epilogue: all 8 gate loads per wave issued up front (saddr form) and consumed behind a counted vmcnt(7) instead of one vmcnt(0) round trip per 4-row group
# speedup vs baseline: 1.0459x; 1.0011x over previous
.LBB0_40:
	s_or_b64 exec, exec, s[12:13]
	s_mul_i32 s8, s7, 0x2800
	s_mul_hi_u32 s9, s6, 0x2800
	s_add_i32 s9, s9, s8
	s_mul_i32 s8, s6, 0x2800
	s_add_u32 s8, s74, s8
	s_addc_u32 s9, s75, s9
	s_lshl_b64 s[6:7], s[6:7], 12
	s_add_u32 s6, s89, s6
	s_waitcnt lgkmcnt(0)
	v_add_u32_e32 v72, s37, v184
	s_addc_u32 s7, s96, s7
	s_lshl_b32 s12, s36, 8
	ds_read_b128 v[64:67], v72
	ds_read_b128 v[68:71], v72 offset:32
	s_add_u32 s8, s8, s12
	s_addc_u32 s9, s9, 0
	s_add_u32 s14, s8, 0x23401800
	s_addc_u32 s15, s9, 0
	v_lshrrev_b32_e32 v130, 4, v160
	v_add_u32_e32 v130, s34, v130
	v_mul_u32_u24_e32 v130, 0x2800, v130
	v_lshlrev_b32_e32 v128, 4, v160
	v_and_b32_e32 v128, 0xf0, v128
	v_add_u32_e32 v130, v130, v128
	global_load_dwordx4 v[96:99], v130, s[14:15]
	v_add_u32_e32 v128, 0xa000, v130
	global_load_dwordx4 v[100:103], v128, s[14:15]
	v_add_u32_e32 v129, 0x14000, v130
	global_load_dwordx4 v[104:107], v129, s[14:15]
	v_add_u32_e32 v128, 0x1e000, v130
	global_load_dwordx4 v[108:111], v128, s[14:15]
	v_add_u32_e32 v129, 0x28000, v130
	global_load_dwordx4 v[112:115], v129, s[14:15]
	v_add_u32_e32 v128, 0x32000, v130
	global_load_dwordx4 v[116:119], v128, s[14:15]
	v_add_u32_e32 v129, 0x3c000, v130
	global_load_dwordx4 v[120:123], v129, s[14:15]
	v_add_u32_e32 v128, 0x46000, v130
	global_load_dwordx4 v[124:127], v128, s[14:15]
	s_waitcnt lgkmcnt(0)
	v_rcp_f32_e32 v73, v64
	v_rcp_f32_e32 v74, v65
	v_rcp_f32_e32 v75, v66
	v_rcp_f32_e32 v76, v67
	ds_read_b128 v[64:67], v72 offset:64
	s_add_u32 s6, s6, s12
	s_addc_u32 s7, s7, 0
	s_lshl_b32 s8, s35, 13
	s_add_i32 s9, s8, 0x8000
	s_cmp_lt_i32 s35, 2
	s_waitcnt lgkmcnt(0)
	v_rcp_f32_e32 v77, v64
	v_rcp_f32_e32 v78, v65
	v_rcp_f32_e32 v79, v66
	v_rcp_f32_e32 v80, v67
	ds_read_b128 v[64:67], v72 offset:96
	s_cselect_b32 s8, s8, s9
	v_lshlrev_b32_e32 v72, 1, v160
	v_lshlrev_b32_e32 v81, 5, v160
	s_add_i32 s12, s8, 0
	v_and_b32_e32 v72, 62, v72
	v_and_b32_e32 v81, 0xfffffc00, v81
	v_mul_f32_e32 v0, v0, v73
	v_add3_u32 v72, s12, v81, v72
	v_mul_f32_e32 v48, v48, v73
	v_cvt_pk_bf16_f32 v0, v0, v48
	ds_write_b16 v72, v0
	ds_write_b16_d16_hi v72, v0 offset:64
	v_mul_f32_e32 v0, v32, v73
	v_mul_f32_e32 v16, v16, v73
	v_cvt_pk_bf16_f32 v0, v0, v16
	ds_write_b16 v72, v0 offset:128
	ds_write_b16_d16_hi v72, v0 offset:192
	v_mul_f32_e32 v0, v1, v74
	v_mul_f32_e32 v1, v49, v74
	v_cvt_pk_bf16_f32 v0, v0, v1
	ds_write_b16 v72, v0 offset:256
	ds_write_b16_d16_hi v72, v0 offset:320
	v_mul_f32_e32 v0, v33, v74
	v_mul_f32_e32 v1, v17, v74
	v_cvt_pk_bf16_f32 v0, v0, v1
	ds_write_b16 v72, v0 offset:384
	ds_write_b16_d16_hi v72, v0 offset:448
	v_mul_f32_e32 v0, v2, v75
	v_mul_f32_e32 v1, v50, v75
	v_cvt_pk_bf16_f32 v0, v0, v1
	ds_write_b16 v72, v0 offset:512
	ds_write_b16_d16_hi v72, v0 offset:576
	v_mul_f32_e32 v0, v34, v75
	v_mul_f32_e32 v1, v18, v75
	v_cvt_pk_bf16_f32 v0, v0, v1
	v_rcp_f32_e32 v68, v68
	ds_write_b16 v72, v0 offset:640
	ds_write_b16_d16_hi v72, v0 offset:704
	v_mul_f32_e32 v0, v3, v76
	v_mul_f32_e32 v1, v51, v76
	v_cvt_pk_bf16_f32 v0, v0, v1
	ds_write_b16 v72, v0 offset:768
	ds_write_b16_d16_hi v72, v0 offset:832
	v_mul_f32_e32 v0, v35, v76
	v_mul_f32_e32 v1, v19, v76
	v_cvt_pk_bf16_f32 v0, v0, v1
	v_rcp_f32_e32 v69, v69
	ds_write_b16 v72, v0 offset:896
	ds_write_b16_d16_hi v72, v0 offset:960
	v_mul_f32_e32 v0, v4, v68
	v_mul_f32_e32 v1, v52, v68
	v_cvt_pk_bf16_f32 v0, v0, v1
	ds_write_b16 v72, v0 offset:2048
	ds_write_b16_d16_hi v72, v0 offset:2112
	v_mul_f32_e32 v0, v36, v68
	v_mul_f32_e32 v1, v20, v68
	v_cvt_pk_bf16_f32 v0, v0, v1
	v_rcp_f32_e32 v70, v70
	ds_write_b16 v72, v0 offset:2176
	ds_write_b16_d16_hi v72, v0 offset:2240
	v_mul_f32_e32 v0, v5, v69
	v_mul_f32_e32 v1, v53, v69
	v_cvt_pk_bf16_f32 v0, v0, v1
	ds_write_b16 v72, v0 offset:2304
	ds_write_b16_d16_hi v72, v0 offset:2368
	v_mul_f32_e32 v0, v37, v69
	v_mul_f32_e32 v1, v21, v69
	v_cvt_pk_bf16_f32 v0, v0, v1
	v_rcp_f32_e32 v71, v71
	ds_write_b16 v72, v0 offset:2432
	ds_write_b16_d16_hi v72, v0 offset:2496
	v_mul_f32_e32 v0, v6, v70
	v_mul_f32_e32 v1, v54, v70
	v_cvt_pk_bf16_f32 v0, v0, v1
	ds_write_b16 v72, v0 offset:2560
	ds_write_b16_d16_hi v72, v0 offset:2624
	v_mul_f32_e32 v0, v38, v70
	v_mul_f32_e32 v1, v22, v70
	v_cvt_pk_bf16_f32 v0, v0, v1
	ds_write_b16 v72, v0 offset:2688
	ds_write_b16_d16_hi v72, v0 offset:2752
	v_mul_f32_e32 v0, v7, v71
	v_mul_f32_e32 v1, v55, v71
	v_cvt_pk_bf16_f32 v0, v0, v1
	ds_write_b16 v72, v0 offset:2816
	ds_write_b16_d16_hi v72, v0 offset:2880
	v_mul_f32_e32 v0, v39, v71
	v_mul_f32_e32 v1, v23, v71
	v_cvt_pk_bf16_f32 v0, v0, v1
	ds_write_b16 v72, v0 offset:2944
	ds_write_b16_d16_hi v72, v0 offset:3008
	v_mul_f32_e32 v0, v8, v77
	v_mul_f32_e32 v1, v56, v77
	v_cvt_pk_bf16_f32 v0, v0, v1
	ds_write_b16 v72, v0 offset:4096
	ds_write_b16_d16_hi v72, v0 offset:4160
	v_mul_f32_e32 v0, v40, v77
	v_mul_f32_e32 v1, v24, v77
	v_cvt_pk_bf16_f32 v0, v0, v1
	ds_write_b16 v72, v0 offset:4224
	ds_write_b16_d16_hi v72, v0 offset:4288
	v_mul_f32_e32 v0, v9, v78
	v_mul_f32_e32 v1, v57, v78
	v_cvt_pk_bf16_f32 v0, v0, v1
	ds_write_b16 v72, v0 offset:4352
	ds_write_b16_d16_hi v72, v0 offset:4416
	v_mul_f32_e32 v0, v41, v78
	v_mul_f32_e32 v1, v25, v78
	v_cvt_pk_bf16_f32 v0, v0, v1
	ds_write_b16 v72, v0 offset:4480
	ds_write_b16_d16_hi v72, v0 offset:4544
	v_mul_f32_e32 v0, v10, v79
	v_mul_f32_e32 v1, v58, v79
	v_cvt_pk_bf16_f32 v0, v0, v1
	ds_write_b16 v72, v0 offset:4608
	ds_write_b16_d16_hi v72, v0 offset:4672
	v_mul_f32_e32 v0, v42, v79
	v_mul_f32_e32 v1, v26, v79
	v_cvt_pk_bf16_f32 v0, v0, v1
	s_waitcnt lgkmcnt(0)
	v_rcp_f32_e32 v64, v64
	ds_write_b16 v72, v0 offset:4736
	ds_write_b16_d16_hi v72, v0 offset:4800
	v_mul_f32_e32 v0, v11, v80
	v_mul_f32_e32 v1, v59, v80
	v_cvt_pk_bf16_f32 v0, v0, v1
	ds_write_b16 v72, v0 offset:4864
	ds_write_b16_d16_hi v72, v0 offset:4928
	v_mul_f32_e32 v0, v43, v80
	v_mul_f32_e32 v1, v27, v80
	v_cvt_pk_bf16_f32 v0, v0, v1
	v_rcp_f32_e32 v65, v65
	ds_write_b16 v72, v0 offset:4992
	ds_write_b16_d16_hi v72, v0 offset:5056
	v_mul_f32_e32 v0, v12, v64
	v_mul_f32_e32 v1, v60, v64
	v_cvt_pk_bf16_f32 v0, v0, v1
	ds_write_b16 v72, v0 offset:6144
	ds_write_b16_d16_hi v72, v0 offset:6208
	v_mul_f32_e32 v0, v44, v64
	v_mul_f32_e32 v1, v28, v64
	v_cvt_pk_bf16_f32 v0, v0, v1
	v_rcp_f32_e32 v66, v66
	ds_write_b16 v72, v0 offset:6272
	ds_write_b16_d16_hi v72, v0 offset:6336
	v_mul_f32_e32 v0, v13, v65
	v_mul_f32_e32 v1, v61, v65
	v_cvt_pk_bf16_f32 v0, v0, v1
	ds_write_b16 v72, v0 offset:6400
	ds_write_b16_d16_hi v72, v0 offset:6464
	v_mul_f32_e32 v0, v45, v65
	v_mul_f32_e32 v1, v29, v65
	v_cvt_pk_bf16_f32 v0, v0, v1
	v_rcp_f32_e32 v67, v67
	ds_write_b16 v72, v0 offset:6528
	ds_write_b16_d16_hi v72, v0 offset:6592
	v_mul_f32_e32 v0, v14, v66
	v_mul_f32_e32 v1, v62, v66
	v_cvt_pk_bf16_f32 v0, v0, v1
	ds_write_b16 v72, v0 offset:6656
	ds_write_b16_d16_hi v72, v0 offset:6720
	v_mul_f32_e32 v0, v46, v66
	v_mul_f32_e32 v1, v30, v66
	v_cvt_pk_bf16_f32 v0, v0, v1
	ds_write_b16 v72, v0 offset:6784
	ds_write_b16_d16_hi v72, v0 offset:6848
	v_mul_f32_e32 v0, v15, v67
	v_mul_f32_e32 v1, v63, v67
	v_cvt_pk_bf16_f32 v0, v0, v1
	ds_write_b16 v72, v0 offset:6912
	ds_write_b16_d16_hi v72, v0 offset:6976
	v_mul_f32_e32 v0, v47, v67
	v_mul_f32_e32 v1, v31, v67
	v_cvt_pk_bf16_f32 v0, v0, v1
	v_ashrrev_i32_e32 v8, 4, v160
	ds_write_b16 v72, v0 offset:7040
	ds_write_b16_d16_hi v72, v0 offset:7104
	v_add_u32_e32 v0, s34, v8
	v_mov_b64_e32 v[2:3], s[14:15]
	v_lshlrev_b32_e32 v4, 4, v160
	v_mad_i64_i32 v[2:3], s[8:9], v0, s90, v[2:3]
	v_and_b32_e32 v184, 0xf0, v4
	s_waitcnt lgkmcnt(0)
	v_lshl_add_u64 v[6:7], v[2:3], 0, v[184:185]
	v_ashrrev_i32_e32 v1, 31, v0
	v_lshlrev_b64 v[0:1], 12, v[0:1]
	v_lshl_add_u64 v[0:1], s[6:7], 0, v[0:1]
	v_lshl_add_u64 v[4:5], v[0:1], 0, v[184:185]
	v_lshlrev_b32_e32 v0, 8, v8
	v_add3_u32 v8, s12, v184, v0
	ds_read_b128 v[0:3], v8
	s_mov_b32 s6, 0xa000
	s_mov_b32 s7, 0x1e000
	v_readlane_b32 s12, v254, 2
	v_readlane_b32 s14, v254, 4
	s_waitcnt lgkmcnt(0)
	v_lshlrev_b32_e32 v9, 16, v0
	v_and_b32_e32 v0, 0xffff0000, v0
	s_add_i32 s46, s46, s14
	s_mov_b32 s70, 0x14000
	s_cmpk_gt_i32 s46, 0x3ff
	v_readlane_b32 s13, v254, 3
	v_readlane_b32 s15, v254, 5
	s_waitcnt vmcnt(7)
	v_mov_b64_e32 v[10:11], v[96:97]
	v_mov_b64_e32 v[12:13], v[98:99]
	v_lshlrev_b32_e32 v14, 16, v10
	v_and_b32_e32 v10, 0xffff0000, v10
	v_mul_f32_e32 v9, v14, v9
	v_mul_f32_e32 v0, v10, v0
	v_cvt_pk_bf16_f32 v0, v9, v0
	v_lshlrev_b32_e32 v9, 16, v1
	v_lshlrev_b32_e32 v10, 16, v11
	v_mul_f32_e32 v9, v10, v9
	v_and_b32_e32 v10, 0xffff0000, v11
	v_and_b32_e32 v1, 0xffff0000, v1
	v_mul_f32_e32 v1, v10, v1
	v_cvt_pk_bf16_f32 v1, v9, v1
	v_lshlrev_b32_e32 v9, 16, v2
	v_lshlrev_b32_e32 v10, 16, v12
	v_mul_f32_e32 v9, v10, v9
	v_and_b32_e32 v10, 0xffff0000, v12
	v_and_b32_e32 v2, 0xffff0000, v2
	v_mul_f32_e32 v2, v10, v2
	v_cvt_pk_bf16_f32 v2, v9, v2
	v_lshlrev_b32_e32 v9, 16, v3
	v_lshlrev_b32_e32 v10, 16, v13
	v_mul_f32_e32 v9, v10, v9
	v_and_b32_e32 v10, 0xffff0000, v13
	v_and_b32_e32 v3, 0xffff0000, v3
	v_mul_f32_e32 v3, v10, v3
	v_add_co_u32_e32 v10, vcc, s6, v6
	v_cvt_pk_bf16_f32 v3, v9, v3
	global_store_dwordx4 v[4:5], v[0:3], off
	s_nop 0
	v_addc_co_u32_e32 v11, vcc, 0, v7, vcc
	ds_read_b128 v[0:3], v8 offset:1024
	s_mov_b32 s6, 0x14000
	s_waitcnt lgkmcnt(0)
	v_lshlrev_b32_e32 v9, 16, v0
	v_and_b32_e32 v0, 0xffff0000, v0
	s_waitcnt vmcnt(7)
	v_mov_b64_e32 v[10:11], v[100:101]
	v_mov_b64_e32 v[12:13], v[102:103]
	v_lshlrev_b32_e32 v14, 16, v10
	v_and_b32_e32 v10, 0xffff0000, v10
	v_mul_f32_e32 v9, v14, v9
	v_mul_f32_e32 v0, v10, v0
	v_cvt_pk_bf16_f32 v0, v9, v0
	v_lshlrev_b32_e32 v9, 16, v1
	v_lshlrev_b32_e32 v10, 16, v11
	v_mul_f32_e32 v9, v10, v9
	v_and_b32_e32 v10, 0xffff0000, v11
	v_and_b32_e32 v1, 0xffff0000, v1
	v_mul_f32_e32 v1, v10, v1
	v_cvt_pk_bf16_f32 v1, v9, v1
	v_lshlrev_b32_e32 v9, 16, v2
	v_lshlrev_b32_e32 v10, 16, v12
	v_mul_f32_e32 v9, v10, v9
	v_and_b32_e32 v10, 0xffff0000, v12
	v_and_b32_e32 v2, 0xffff0000, v2
	v_mul_f32_e32 v2, v10, v2
	v_cvt_pk_bf16_f32 v2, v9, v2
	v_lshlrev_b32_e32 v9, 16, v3
	v_lshlrev_b32_e32 v10, 16, v13
	v_mul_f32_e32 v9, v10, v9
	v_and_b32_e32 v10, 0xffff0000, v13
	v_and_b32_e32 v3, 0xffff0000, v3
	v_mul_f32_e32 v3, v10, v3
	v_add_co_u32_e32 v10, vcc, s92, v4
	v_cvt_pk_bf16_f32 v3, v9, v3
	s_nop 1
	v_addc_co_u32_e32 v11, vcc, 0, v5, vcc
	global_store_dwordx4 v[10:11], v[0:3], off
	v_add_co_u32_e32 v10, vcc, s6, v6
	ds_read_b128 v[0:3], v8 offset:2048
	s_nop 0
	v_addc_co_u32_e32 v11, vcc, 0, v7, vcc
	s_waitcnt lgkmcnt(0)
	v_lshlrev_b32_e32 v9, 16, v0
	v_and_b32_e32 v0, 0xffff0000, v0
	s_waitcnt vmcnt(7)
	v_mov_b64_e32 v[10:11], v[104:105]
	v_mov_b64_e32 v[12:13], v[106:107]
	v_lshlrev_b32_e32 v14, 16, v10
	v_and_b32_e32 v10, 0xffff0000, v10
	v_mul_f32_e32 v9, v14, v9
	v_mul_f32_e32 v0, v10, v0
	v_cvt_pk_bf16_f32 v0, v9, v0
	v_lshlrev_b32_e32 v9, 16, v1
	v_lshlrev_b32_e32 v10, 16, v11
	v_mul_f32_e32 v9, v10, v9
	v_and_b32_e32 v10, 0xffff0000, v11
	v_and_b32_e32 v1, 0xffff0000, v1
	v_mul_f32_e32 v1, v10, v1
	v_cvt_pk_bf16_f32 v1, v9, v1
	v_lshlrev_b32_e32 v9, 16, v2
	v_lshlrev_b32_e32 v10, 16, v12
	v_mul_f32_e32 v9, v10, v9
	v_and_b32_e32 v10, 0xffff0000, v12
	v_and_b32_e32 v2, 0xffff0000, v2
	v_mul_f32_e32 v2, v10, v2
	v_cvt_pk_bf16_f32 v2, v9, v2
	v_lshlrev_b32_e32 v9, 16, v3
	v_lshlrev_b32_e32 v10, 16, v13
	v_mul_f32_e32 v9, v10, v9
	v_and_b32_e32 v10, 0xffff0000, v13
	v_and_b32_e32 v3, 0xffff0000, v3
	v_mul_f32_e32 v3, v10, v3
	v_add_co_u32_e32 v10, vcc, s77, v4
	v_cvt_pk_bf16_f32 v3, v9, v3
	s_nop 1
	v_addc_co_u32_e32 v11, vcc, 0, v5, vcc
	global_store_dwordx4 v[10:11], v[0:3], off
	v_add_co_u32_e32 v10, vcc, s7, v6
	ds_read_b128 v[0:3], v8 offset:3072
	s_nop 0
	v_addc_co_u32_e32 v11, vcc, 0, v7, vcc
	s_mov_b32 s7, 0xc000
	s_waitcnt lgkmcnt(0)
	v_lshlrev_b32_e32 v9, 16, v0
	v_and_b32_e32 v0, 0xffff0000, v0
	s_waitcnt vmcnt(7)
	v_mov_b64_e32 v[10:11], v[108:109]
	v_mov_b64_e32 v[12:13], v[110:111]
	v_lshlrev_b32_e32 v14, 16, v10
	v_and_b32_e32 v10, 0xffff0000, v10
	v_mul_f32_e32 v9, v14, v9
	v_mul_f32_e32 v0, v10, v0
	v_cvt_pk_bf16_f32 v0, v9, v0
	v_lshlrev_b32_e32 v9, 16, v1
	v_lshlrev_b32_e32 v10, 16, v11
	v_mul_f32_e32 v9, v10, v9
	v_and_b32_e32 v10, 0xffff0000, v11
	v_and_b32_e32 v1, 0xffff0000, v1
	v_mul_f32_e32 v1, v10, v1
	v_cvt_pk_bf16_f32 v1, v9, v1
	v_lshlrev_b32_e32 v9, 16, v2
	v_lshlrev_b32_e32 v10, 16, v12
	v_mul_f32_e32 v9, v10, v9
	v_and_b32_e32 v10, 0xffff0000, v12
	v_and_b32_e32 v2, 0xffff0000, v2
	v_mul_f32_e32 v2, v10, v2
	v_cvt_pk_bf16_f32 v2, v9, v2
	v_lshlrev_b32_e32 v9, 16, v3
	v_lshlrev_b32_e32 v10, 16, v13
	v_mul_f32_e32 v9, v10, v9
	v_and_b32_e32 v10, 0xffff0000, v13
	v_and_b32_e32 v3, 0xffff0000, v3
	v_mul_f32_e32 v3, v10, v3
	v_add_co_u32_e32 v10, vcc, s7, v4
	s_mov_b32 s7, 0x28000
	s_nop 0
	v_addc_co_u32_e32 v11, vcc, 0, v5, vcc
	v_cvt_pk_bf16_f32 v3, v9, v3
	global_store_dwordx4 v[10:11], v[0:3], off
	v_add_co_u32_e32 v10, vcc, s7, v6
	ds_read_b128 v[0:3], v8 offset:4096
	s_nop 0
	v_addc_co_u32_e32 v11, vcc, 0, v7, vcc
	s_mov_b32 s7, 0x32000
	s_waitcnt lgkmcnt(0)
	v_lshlrev_b32_e32 v9, 16, v0
	v_and_b32_e32 v0, 0xffff0000, v0
	s_waitcnt vmcnt(7)
	v_mov_b64_e32 v[10:11], v[112:113]
	v_mov_b64_e32 v[12:13], v[114:115]
	v_lshlrev_b32_e32 v14, 16, v10
	v_and_b32_e32 v10, 0xffff0000, v10
	v_mul_f32_e32 v9, v14, v9
	v_mul_f32_e32 v0, v10, v0
	v_cvt_pk_bf16_f32 v0, v9, v0
	v_lshlrev_b32_e32 v9, 16, v1
	v_lshlrev_b32_e32 v10, 16, v11
	v_mul_f32_e32 v9, v10, v9
	v_and_b32_e32 v10, 0xffff0000, v11
	v_and_b32_e32 v1, 0xffff0000, v1
	v_mul_f32_e32 v1, v10, v1
	v_cvt_pk_bf16_f32 v1, v9, v1
	v_lshlrev_b32_e32 v9, 16, v2
	v_lshlrev_b32_e32 v10, 16, v12
	v_mul_f32_e32 v9, v10, v9
	v_and_b32_e32 v10, 0xffff0000, v12
	v_and_b32_e32 v2, 0xffff0000, v2
	v_mul_f32_e32 v2, v10, v2
	v_cvt_pk_bf16_f32 v2, v9, v2
	v_lshlrev_b32_e32 v9, 16, v3
	v_lshlrev_b32_e32 v10, 16, v13
	v_mul_f32_e32 v9, v10, v9
	v_and_b32_e32 v10, 0xffff0000, v13
	v_and_b32_e32 v3, 0xffff0000, v3
	v_mul_f32_e32 v3, v10, v3
	v_add_co_u32_e32 v10, vcc, s72, v4
	v_cvt_pk_bf16_f32 v3, v9, v3
	s_nop 1
	v_addc_co_u32_e32 v11, vcc, 0, v5, vcc
	global_store_dwordx4 v[10:11], v[0:3], off
	v_add_co_u32_e32 v10, vcc, s7, v6
	ds_read_b128 v[0:3], v8 offset:5120
	s_nop 0
	v_addc_co_u32_e32 v11, vcc, 0, v7, vcc
	s_waitcnt lgkmcnt(0)
	v_lshlrev_b32_e32 v9, 16, v0
	v_and_b32_e32 v0, 0xffff0000, v0
	s_waitcnt vmcnt(7)
	v_mov_b64_e32 v[10:11], v[116:117]
	v_mov_b64_e32 v[12:13], v[118:119]
	v_lshlrev_b32_e32 v14, 16, v10
	v_and_b32_e32 v10, 0xffff0000, v10
	v_mul_f32_e32 v9, v14, v9
	v_mul_f32_e32 v0, v10, v0
	v_cvt_pk_bf16_f32 v0, v9, v0
	v_lshlrev_b32_e32 v9, 16, v1
	v_lshlrev_b32_e32 v10, 16, v11
	v_mul_f32_e32 v9, v10, v9
	v_and_b32_e32 v10, 0xffff0000, v11
	v_and_b32_e32 v1, 0xffff0000, v1
	v_mul_f32_e32 v1, v10, v1
	v_cvt_pk_bf16_f32 v1, v9, v1
	v_lshlrev_b32_e32 v9, 16, v2
	v_lshlrev_b32_e32 v10, 16, v12
	v_mul_f32_e32 v9, v10, v9
	v_and_b32_e32 v10, 0xffff0000, v12
	v_and_b32_e32 v2, 0xffff0000, v2
	v_mul_f32_e32 v2, v10, v2
	v_cvt_pk_bf16_f32 v2, v9, v2
	v_lshlrev_b32_e32 v9, 16, v3
	v_lshlrev_b32_e32 v10, 16, v13
	v_mul_f32_e32 v9, v10, v9
	v_and_b32_e32 v10, 0xffff0000, v13
	v_and_b32_e32 v3, 0xffff0000, v3
	v_mul_f32_e32 v3, v10, v3
	v_add_co_u32_e32 v10, vcc, s6, v4
	s_mov_b32 s6, 0x3c000
	s_nop 0
	v_addc_co_u32_e32 v11, vcc, 0, v5, vcc
	v_cvt_pk_bf16_f32 v3, v9, v3
	global_store_dwordx4 v[10:11], v[0:3], off
	v_add_co_u32_e32 v10, vcc, s6, v6
	ds_read_b128 v[0:3], v8 offset:6144
	s_nop 0
	v_addc_co_u32_e32 v11, vcc, 0, v7, vcc
	s_mov_b32 s6, 0x18000
	s_waitcnt lgkmcnt(0)
	v_lshlrev_b32_e32 v9, 16, v0
	v_and_b32_e32 v0, 0xffff0000, v0
	s_waitcnt vmcnt(7)
	v_mov_b64_e32 v[10:11], v[120:121]
	v_mov_b64_e32 v[12:13], v[122:123]
	v_lshlrev_b32_e32 v14, 16, v10
	v_and_b32_e32 v10, 0xffff0000, v10
	v_mul_f32_e32 v9, v14, v9
	v_mul_f32_e32 v0, v10, v0
	v_cvt_pk_bf16_f32 v0, v9, v0
	v_lshlrev_b32_e32 v9, 16, v1
	v_lshlrev_b32_e32 v10, 16, v11
	v_mul_f32_e32 v9, v10, v9
	v_and_b32_e32 v10, 0xffff0000, v11
	v_and_b32_e32 v1, 0xffff0000, v1
	v_mul_f32_e32 v1, v10, v1
	v_cvt_pk_bf16_f32 v1, v9, v1
	v_lshlrev_b32_e32 v9, 16, v2
	v_lshlrev_b32_e32 v10, 16, v12
	v_mul_f32_e32 v9, v10, v9
	v_and_b32_e32 v10, 0xffff0000, v12
	v_and_b32_e32 v2, 0xffff0000, v2
	v_mul_f32_e32 v2, v10, v2
	v_cvt_pk_bf16_f32 v2, v9, v2
	v_lshlrev_b32_e32 v9, 16, v3
	v_lshlrev_b32_e32 v10, 16, v13
	v_mul_f32_e32 v9, v10, v9
	v_and_b32_e32 v10, 0xffff0000, v13
	v_and_b32_e32 v3, 0xffff0000, v3
	v_mul_f32_e32 v3, v10, v3
	v_add_co_u32_e32 v10, vcc, s6, v4
	s_mov_b32 s6, 0x46000
	s_nop 0
	v_addc_co_u32_e32 v11, vcc, 0, v5, vcc
	v_add_co_u32_e32 v6, vcc, s6, v6
	v_cvt_pk_bf16_f32 v3, v9, v3
	global_store_dwordx4 v[10:11], v[0:3], off
	s_nop 0
	v_addc_co_u32_e32 v7, vcc, 0, v7, vcc
	ds_read_b128 v[0:3], v8 offset:7168
	v_add_co_u32_e32 v4, vcc, 0x1c000, v4
	s_waitcnt lgkmcnt(0)
	v_lshlrev_b32_e32 v10, 16, v0
	v_and_b32_e32 v0, 0xffff0000, v0
	v_addc_co_u32_e32 v5, vcc, 0, v5, vcc
	s_waitcnt vmcnt(7)
	v_mov_b64_e32 v[6:7], v[124:125]
	v_mov_b64_e32 v[8:9], v[126:127]
	v_lshlrev_b32_e32 v11, 16, v6
	v_and_b32_e32 v6, 0xffff0000, v6
	v_mul_f32_e32 v10, v11, v10
	v_mul_f32_e32 v0, v6, v0
	v_cvt_pk_bf16_f32 v0, v10, v0
	v_lshlrev_b32_e32 v6, 16, v1
	v_lshlrev_b32_e32 v10, 16, v7
	v_and_b32_e32 v7, 0xffff0000, v7
	v_and_b32_e32 v1, 0xffff0000, v1
	v_mul_f32_e32 v6, v10, v6
	v_mul_f32_e32 v1, v7, v1
	v_cvt_pk_bf16_f32 v1, v6, v1
	v_lshlrev_b32_e32 v6, 16, v2
	v_lshlrev_b32_e32 v7, 16, v8
	v_mul_f32_e32 v6, v7, v6
	v_and_b32_e32 v7, 0xffff0000, v8
	v_and_b32_e32 v2, 0xffff0000, v2
	v_mul_f32_e32 v2, v7, v2
	v_cvt_pk_bf16_f32 v2, v6, v2
	v_lshlrev_b32_e32 v6, 16, v3
	v_lshlrev_b32_e32 v7, 16, v9
	v_mul_f32_e32 v6, v7, v6
	v_and_b32_e32 v7, 0xffff0000, v9
	v_and_b32_e32 v3, 0xffff0000, v3
	v_mul_f32_e32 v3, v7, v3
	v_cvt_pk_bf16_f32 v3, v6, v3
	global_store_dwordx4 v[4:5], v[0:3], off
	s_barrier
	s_cbranch_scc1 .LBB0_59
